# SSD state pass (m3): decay/state loads for 8 chunks per batch with two batches in flight ahead of the serial recurrence; chunk order and arithmetic unchanged
# speedup vs baseline: 1.0111x; 1.0025x over previous
.LBB0_729:
	v_lshlrev_b32_e32 v2, 1, v8
	v_ashrrev_i32_e32 v6, 15, v8
	v_and_b32_e32 v4, 0xc000, v2
	v_and_b32_e32 v2, 0x1fff, v9
	v_lshlrev_b32_e32 v3, 2, v8
	v_ashrrev_i32_e32 v7, 31, v6
	v_lshlrev_b32_e32 v5, 1, v2
	v_and_b32_e32 v12, 0x18000, v3
	v_lshlrev_b32_e32 v13, 2, v2
	v_lshlrev_b64 v[2:3], 22, v[6:7]
	v_lshrrev_b32_e32 v10, 11, v8
	v_or3_b32 v2, v2, v4, v5
	v_lshlrev_b64 v[4:5], 10, v[6:7]
	v_lshlrev_b64 v[6:7], 23, v[6:7]
	v_and_or_b32 v4, v10, 12, v4
	v_or3_b32 v6, v6, v12, v13
	v_mov_b32_e32 v12, 0
	s_mov_b32 s2, -8
	s_waitcnt lgkmcnt(0)
	v_lshl_add_u64 v[74:75], s[8:9], 0, v[6:7]
	v_add_co_u32_e32 v74, vcc, 0x16100000, v74
	v_addc_co_u32_e32 v75, vcc, 0, v75, vcc
	v_lshl_add_u64 v[76:77], s[8:9], 0, v[4:5]
	v_add_co_u32_e32 v76, vcc, 0xc0000, v76
	v_addc_co_u32_e32 v77, vcc, 0, v77, vcc
	v_lshl_add_u64 v[78:79], s[8:9], 0, v[2:3]
	v_add_co_u32_e32 v78, vcc, 0x17100000, v78
	v_addc_co_u32_e32 v79, vcc, 0, v79, vcc
	global_load_dword v26, v[74:75], off
	v_add_co_u32_e32 v74, vcc, 0x20000, v74
	v_addc_co_u32_e32 v75, vcc, 0, v75, vcc
	global_load_dword v50, v[76:77], off
	global_load_dword v27, v[74:75], off
	v_add_co_u32_e32 v74, vcc, 0x20000, v74
	v_addc_co_u32_e32 v75, vcc, 0, v75, vcc
	global_load_dword v51, v[76:77], off offset:16
	global_load_dword v28, v[74:75], off
	v_add_co_u32_e32 v74, vcc, 0x20000, v74
	v_addc_co_u32_e32 v75, vcc, 0, v75, vcc
	global_load_dword v52, v[76:77], off offset:32
	global_load_dword v29, v[74:75], off
	v_add_co_u32_e32 v74, vcc, 0x20000, v74
	v_addc_co_u32_e32 v75, vcc, 0, v75, vcc
	global_load_dword v53, v[76:77], off offset:48
	global_load_dword v30, v[74:75], off
	v_add_co_u32_e32 v74, vcc, 0x20000, v74
	v_addc_co_u32_e32 v75, vcc, 0, v75, vcc
	global_load_dword v54, v[76:77], off offset:64
	global_load_dword v31, v[74:75], off
	v_add_co_u32_e32 v74, vcc, 0x20000, v74
	v_addc_co_u32_e32 v75, vcc, 0, v75, vcc
	global_load_dword v55, v[76:77], off offset:80
	global_load_dword v32, v[74:75], off
	v_add_co_u32_e32 v74, vcc, 0x20000, v74
	v_addc_co_u32_e32 v75, vcc, 0, v75, vcc
	global_load_dword v56, v[76:77], off offset:96
	global_load_dword v33, v[74:75], off
	v_add_co_u32_e32 v74, vcc, 0x20000, v74
	v_addc_co_u32_e32 v75, vcc, 0, v75, vcc
	global_load_dword v57, v[76:77], off offset:112
	global_load_dword v34, v[74:75], off
	v_add_co_u32_e32 v74, vcc, 0x20000, v74
	v_addc_co_u32_e32 v75, vcc, 0, v75, vcc
	global_load_dword v58, v[76:77], off offset:128
	global_load_dword v35, v[74:75], off
	v_add_co_u32_e32 v74, vcc, 0x20000, v74
	v_addc_co_u32_e32 v75, vcc, 0, v75, vcc
	global_load_dword v59, v[76:77], off offset:144
	global_load_dword v36, v[74:75], off
	v_add_co_u32_e32 v74, vcc, 0x20000, v74
	v_addc_co_u32_e32 v75, vcc, 0, v75, vcc
	global_load_dword v60, v[76:77], off offset:160
	global_load_dword v37, v[74:75], off
	v_add_co_u32_e32 v74, vcc, 0x20000, v74
	v_addc_co_u32_e32 v75, vcc, 0, v75, vcc
	global_load_dword v61, v[76:77], off offset:176
	global_load_dword v38, v[74:75], off
	v_add_co_u32_e32 v74, vcc, 0x20000, v74
	v_addc_co_u32_e32 v75, vcc, 0, v75, vcc
	global_load_dword v62, v[76:77], off offset:192
	global_load_dword v39, v[74:75], off
	v_add_co_u32_e32 v74, vcc, 0x20000, v74
	v_addc_co_u32_e32 v75, vcc, 0, v75, vcc
	global_load_dword v63, v[76:77], off offset:208
	global_load_dword v40, v[74:75], off
	v_add_co_u32_e32 v74, vcc, 0x20000, v74
	v_addc_co_u32_e32 v75, vcc, 0, v75, vcc
	global_load_dword v64, v[76:77], off offset:224
	global_load_dword v41, v[74:75], off
	v_add_co_u32_e32 v74, vcc, 0x20000, v74
	v_addc_co_u32_e32 v75, vcc, 0, v75, vcc
	global_load_dword v65, v[76:77], off offset:240
	global_load_dword v42, v[74:75], off
	v_add_co_u32_e32 v74, vcc, 0x20000, v74
	v_addc_co_u32_e32 v75, vcc, 0, v75, vcc
	global_load_dword v66, v[76:77], off offset:256
	global_load_dword v43, v[74:75], off
	v_add_co_u32_e32 v74, vcc, 0x20000, v74
	v_addc_co_u32_e32 v75, vcc, 0, v75, vcc
	global_load_dword v67, v[76:77], off offset:272
	global_load_dword v44, v[74:75], off
	v_add_co_u32_e32 v74, vcc, 0x20000, v74
	v_addc_co_u32_e32 v75, vcc, 0, v75, vcc
	global_load_dword v68, v[76:77], off offset:288
	global_load_dword v45, v[74:75], off
	v_add_co_u32_e32 v74, vcc, 0x20000, v74
	v_addc_co_u32_e32 v75, vcc, 0, v75, vcc
	global_load_dword v69, v[76:77], off offset:304
	global_load_dword v46, v[74:75], off
	v_add_co_u32_e32 v74, vcc, 0x20000, v74
	v_addc_co_u32_e32 v75, vcc, 0, v75, vcc
	global_load_dword v70, v[76:77], off offset:320
	global_load_dword v47, v[74:75], off
	v_add_co_u32_e32 v74, vcc, 0x20000, v74
	v_addc_co_u32_e32 v75, vcc, 0, v75, vcc
	global_load_dword v71, v[76:77], off offset:336
	global_load_dword v48, v[74:75], off
	v_add_co_u32_e32 v74, vcc, 0x20000, v74
	v_addc_co_u32_e32 v75, vcc, 0, v75, vcc
	global_load_dword v72, v[76:77], off offset:352
	global_load_dword v49, v[74:75], off
	v_add_co_u32_e32 v74, vcc, 0x20000, v74
	v_addc_co_u32_e32 v75, vcc, 0, v75, vcc
	global_load_dword v73, v[76:77], off offset:368
	s_waitcnt vmcnt(32)
	v_cvt_pk_bf16_f32 v80, v12, v11
	v_mul_f32_e32 v81, 0x3fb8aa3b, v50
	global_store_short v[78:79], v80, off
	v_exp_f32_e32 v81, v81
	v_add_co_u32_e32 v78, vcc, 0x10000, v78
	v_addc_co_u32_e32 v79, vcc, 0, v79, vcc
	v_fmac_f32_e32 v26, v12, v81
	v_cvt_pk_bf16_f32 v80, v26, v11
	v_mul_f32_e32 v81, 0x3fb8aa3b, v51
	global_store_short v[78:79], v80, off
	v_exp_f32_e32 v81, v81
	v_add_co_u32_e32 v78, vcc, 0x10000, v78
	v_addc_co_u32_e32 v79, vcc, 0, v79, vcc
	v_fmac_f32_e32 v27, v26, v81
	v_cvt_pk_bf16_f32 v80, v27, v11
	v_mul_f32_e32 v81, 0x3fb8aa3b, v52
	global_store_short v[78:79], v80, off
	v_exp_f32_e32 v81, v81
	v_add_co_u32_e32 v78, vcc, 0x10000, v78
	v_addc_co_u32_e32 v79, vcc, 0, v79, vcc
	v_fmac_f32_e32 v28, v27, v81
	v_cvt_pk_bf16_f32 v80, v28, v11
	v_mul_f32_e32 v81, 0x3fb8aa3b, v53
	global_store_short v[78:79], v80, off
	v_exp_f32_e32 v81, v81
	v_add_co_u32_e32 v78, vcc, 0x10000, v78
	v_addc_co_u32_e32 v79, vcc, 0, v79, vcc
	v_fmac_f32_e32 v29, v28, v81
	v_cvt_pk_bf16_f32 v80, v29, v11
	v_mul_f32_e32 v81, 0x3fb8aa3b, v54
	global_store_short v[78:79], v80, off
	v_exp_f32_e32 v81, v81
	v_add_co_u32_e32 v78, vcc, 0x10000, v78
	v_addc_co_u32_e32 v79, vcc, 0, v79, vcc
	v_fmac_f32_e32 v30, v29, v81
	v_cvt_pk_bf16_f32 v80, v30, v11
	v_mul_f32_e32 v81, 0x3fb8aa3b, v55
	global_store_short v[78:79], v80, off
	v_exp_f32_e32 v81, v81
	v_add_co_u32_e32 v78, vcc, 0x10000, v78
	v_addc_co_u32_e32 v79, vcc, 0, v79, vcc
	v_fmac_f32_e32 v31, v30, v81
	v_cvt_pk_bf16_f32 v80, v31, v11
	v_mul_f32_e32 v81, 0x3fb8aa3b, v56
	global_store_short v[78:79], v80, off
	v_exp_f32_e32 v81, v81
	v_add_co_u32_e32 v78, vcc, 0x10000, v78
	v_addc_co_u32_e32 v79, vcc, 0, v79, vcc
	v_fmac_f32_e32 v32, v31, v81
	v_cvt_pk_bf16_f32 v80, v32, v11
	v_mul_f32_e32 v81, 0x3fb8aa3b, v57
	global_store_short v[78:79], v80, off
	v_exp_f32_e32 v81, v81
	v_add_co_u32_e32 v78, vcc, 0x10000, v78
	v_addc_co_u32_e32 v79, vcc, 0, v79, vcc
	v_fmac_f32_e32 v33, v32, v81
	global_load_dword v26, v[74:75], off
	v_add_co_u32_e32 v74, vcc, 0x20000, v74
	v_addc_co_u32_e32 v75, vcc, 0, v75, vcc
	global_load_dword v50, v[76:77], off offset:384
	global_load_dword v27, v[74:75], off
	v_add_co_u32_e32 v74, vcc, 0x20000, v74
	v_addc_co_u32_e32 v75, vcc, 0, v75, vcc
	global_load_dword v51, v[76:77], off offset:400
	global_load_dword v28, v[74:75], off
	v_add_co_u32_e32 v74, vcc, 0x20000, v74
	v_addc_co_u32_e32 v75, vcc, 0, v75, vcc
	global_load_dword v52, v[76:77], off offset:416
	global_load_dword v29, v[74:75], off
	v_add_co_u32_e32 v74, vcc, 0x20000, v74
	v_addc_co_u32_e32 v75, vcc, 0, v75, vcc
	global_load_dword v53, v[76:77], off offset:432
	global_load_dword v30, v[74:75], off
	v_add_co_u32_e32 v74, vcc, 0x20000, v74
	v_addc_co_u32_e32 v75, vcc, 0, v75, vcc
	global_load_dword v54, v[76:77], off offset:448
	global_load_dword v31, v[74:75], off
	v_add_co_u32_e32 v74, vcc, 0x20000, v74
	v_addc_co_u32_e32 v75, vcc, 0, v75, vcc
	global_load_dword v55, v[76:77], off offset:464
	global_load_dword v32, v[74:75], off
	v_add_co_u32_e32 v74, vcc, 0x20000, v74
	v_addc_co_u32_e32 v75, vcc, 0, v75, vcc
	global_load_dword v56, v[76:77], off offset:480
	global_load_dword v33, v[74:75], off
	v_add_co_u32_e32 v74, vcc, 0x20000, v74
	v_addc_co_u32_e32 v75, vcc, 0, v75, vcc
	global_load_dword v57, v[76:77], off offset:496
	s_waitcnt vmcnt(40)
	v_cvt_pk_bf16_f32 v80, v33, v11
	v_mul_f32_e32 v81, 0x3fb8aa3b, v58
	global_store_short v[78:79], v80, off
	v_exp_f32_e32 v81, v81
	v_add_co_u32_e32 v78, vcc, 0x10000, v78
	v_addc_co_u32_e32 v79, vcc, 0, v79, vcc
	v_fmac_f32_e32 v34, v33, v81
	v_cvt_pk_bf16_f32 v80, v34, v11
	v_mul_f32_e32 v81, 0x3fb8aa3b, v59
	global_store_short v[78:79], v80, off
	v_exp_f32_e32 v81, v81
	v_add_co_u32_e32 v78, vcc, 0x10000, v78
	v_addc_co_u32_e32 v79, vcc, 0, v79, vcc
	v_fmac_f32_e32 v35, v34, v81
	v_cvt_pk_bf16_f32 v80, v35, v11
	v_mul_f32_e32 v81, 0x3fb8aa3b, v60
	global_store_short v[78:79], v80, off
	v_exp_f32_e32 v81, v81
	v_add_co_u32_e32 v78, vcc, 0x10000, v78
	v_addc_co_u32_e32 v79, vcc, 0, v79, vcc
	v_fmac_f32_e32 v36, v35, v81
	v_cvt_pk_bf16_f32 v80, v36, v11
	v_mul_f32_e32 v81, 0x3fb8aa3b, v61
	global_store_short v[78:79], v80, off
	v_exp_f32_e32 v81, v81
	v_add_co_u32_e32 v78, vcc, 0x10000, v78
	v_addc_co_u32_e32 v79, vcc, 0, v79, vcc
	v_fmac_f32_e32 v37, v36, v81
	v_cvt_pk_bf16_f32 v80, v37, v11
	v_mul_f32_e32 v81, 0x3fb8aa3b, v62
	global_store_short v[78:79], v80, off
	v_exp_f32_e32 v81, v81
	v_add_co_u32_e32 v78, vcc, 0x10000, v78
	v_addc_co_u32_e32 v79, vcc, 0, v79, vcc
	v_fmac_f32_e32 v38, v37, v81
	v_cvt_pk_bf16_f32 v80, v38, v11
	v_mul_f32_e32 v81, 0x3fb8aa3b, v63
	global_store_short v[78:79], v80, off
	v_exp_f32_e32 v81, v81
	v_add_co_u32_e32 v78, vcc, 0x10000, v78
	v_addc_co_u32_e32 v79, vcc, 0, v79, vcc
	v_fmac_f32_e32 v39, v38, v81
	v_cvt_pk_bf16_f32 v80, v39, v11
	v_mul_f32_e32 v81, 0x3fb8aa3b, v64
	global_store_short v[78:79], v80, off
	v_exp_f32_e32 v81, v81
	v_add_co_u32_e32 v78, vcc, 0x10000, v78
	v_addc_co_u32_e32 v79, vcc, 0, v79, vcc
	v_fmac_f32_e32 v40, v39, v81
	v_cvt_pk_bf16_f32 v80, v40, v11
	v_mul_f32_e32 v81, 0x3fb8aa3b, v65
	global_store_short v[78:79], v80, off
	v_exp_f32_e32 v81, v81
	v_add_co_u32_e32 v78, vcc, 0x10000, v78
	v_addc_co_u32_e32 v79, vcc, 0, v79, vcc
	v_fmac_f32_e32 v41, v40, v81
	global_load_dword v34, v[74:75], off
	v_add_co_u32_e32 v74, vcc, 0x20000, v74
	v_addc_co_u32_e32 v75, vcc, 0, v75, vcc
	global_load_dword v58, v[76:77], off offset:512
	global_load_dword v35, v[74:75], off
	v_add_co_u32_e32 v74, vcc, 0x20000, v74
	v_addc_co_u32_e32 v75, vcc, 0, v75, vcc
	global_load_dword v59, v[76:77], off offset:528
	global_load_dword v36, v[74:75], off
	v_add_co_u32_e32 v74, vcc, 0x20000, v74
	v_addc_co_u32_e32 v75, vcc, 0, v75, vcc
	global_load_dword v60, v[76:77], off offset:544
	global_load_dword v37, v[74:75], off
	v_add_co_u32_e32 v74, vcc, 0x20000, v74
	v_addc_co_u32_e32 v75, vcc, 0, v75, vcc
	global_load_dword v61, v[76:77], off offset:560
	global_load_dword v38, v[74:75], off
	v_add_co_u32_e32 v74, vcc, 0x20000, v74
	v_addc_co_u32_e32 v75, vcc, 0, v75, vcc
	global_load_dword v62, v[76:77], off offset:576
	global_load_dword v39, v[74:75], off
	v_add_co_u32_e32 v74, vcc, 0x20000, v74
	v_addc_co_u32_e32 v75, vcc, 0, v75, vcc
	global_load_dword v63, v[76:77], off offset:592
	global_load_dword v40, v[74:75], off
	v_add_co_u32_e32 v74, vcc, 0x20000, v74
	v_addc_co_u32_e32 v75, vcc, 0, v75, vcc
	global_load_dword v64, v[76:77], off offset:608
	global_load_dword v41, v[74:75], off
	v_add_co_u32_e32 v74, vcc, 0x20000, v74
	v_addc_co_u32_e32 v75, vcc, 0, v75, vcc
	global_load_dword v65, v[76:77], off offset:624
	s_waitcnt vmcnt(40)
	v_cvt_pk_bf16_f32 v80, v41, v11
	v_mul_f32_e32 v81, 0x3fb8aa3b, v66
	global_store_short v[78:79], v80, off
	v_exp_f32_e32 v81, v81
	v_add_co_u32_e32 v78, vcc, 0x10000, v78
	v_addc_co_u32_e32 v79, vcc, 0, v79, vcc
	v_fmac_f32_e32 v42, v41, v81
	v_cvt_pk_bf16_f32 v80, v42, v11
	v_mul_f32_e32 v81, 0x3fb8aa3b, v67
	global_store_short v[78:79], v80, off
	v_exp_f32_e32 v81, v81
	v_add_co_u32_e32 v78, vcc, 0x10000, v78
	v_addc_co_u32_e32 v79, vcc, 0, v79, vcc
	v_fmac_f32_e32 v43, v42, v81
	v_cvt_pk_bf16_f32 v80, v43, v11
	v_mul_f32_e32 v81, 0x3fb8aa3b, v68
	global_store_short v[78:79], v80, off
	v_exp_f32_e32 v81, v81
	v_add_co_u32_e32 v78, vcc, 0x10000, v78
	v_addc_co_u32_e32 v79, vcc, 0, v79, vcc
	v_fmac_f32_e32 v44, v43, v81
	v_cvt_pk_bf16_f32 v80, v44, v11
	v_mul_f32_e32 v81, 0x3fb8aa3b, v69
	global_store_short v[78:79], v80, off
	v_exp_f32_e32 v81, v81
	v_add_co_u32_e32 v78, vcc, 0x10000, v78
	v_addc_co_u32_e32 v79, vcc, 0, v79, vcc
	v_fmac_f32_e32 v45, v44, v81
	v_cvt_pk_bf16_f32 v80, v45, v11
	v_mul_f32_e32 v81, 0x3fb8aa3b, v70
	global_store_short v[78:79], v80, off
	v_exp_f32_e32 v81, v81
	v_add_co_u32_e32 v78, vcc, 0x10000, v78
	v_addc_co_u32_e32 v79, vcc, 0, v79, vcc
	v_fmac_f32_e32 v46, v45, v81
	v_cvt_pk_bf16_f32 v80, v46, v11
	v_mul_f32_e32 v81, 0x3fb8aa3b, v71
	global_store_short v[78:79], v80, off
	v_exp_f32_e32 v81, v81
	v_add_co_u32_e32 v78, vcc, 0x10000, v78
	v_addc_co_u32_e32 v79, vcc, 0, v79, vcc
	v_fmac_f32_e32 v47, v46, v81
	v_cvt_pk_bf16_f32 v80, v47, v11
	v_mul_f32_e32 v81, 0x3fb8aa3b, v72
	global_store_short v[78:79], v80, off
	v_exp_f32_e32 v81, v81
	v_add_co_u32_e32 v78, vcc, 0x10000, v78
	v_addc_co_u32_e32 v79, vcc, 0, v79, vcc
	v_fmac_f32_e32 v48, v47, v81
	v_cvt_pk_bf16_f32 v80, v48, v11
	v_mul_f32_e32 v81, 0x3fb8aa3b, v73
	global_store_short v[78:79], v80, off
	v_exp_f32_e32 v81, v81
	v_add_co_u32_e32 v78, vcc, 0x10000, v78
	v_addc_co_u32_e32 v79, vcc, 0, v79, vcc
	v_fmac_f32_e32 v49, v48, v81
	global_load_dword v42, v[74:75], off
	v_add_co_u32_e32 v74, vcc, 0x20000, v74
	v_addc_co_u32_e32 v75, vcc, 0, v75, vcc
	global_load_dword v66, v[76:77], off offset:640
	global_load_dword v43, v[74:75], off
	v_add_co_u32_e32 v74, vcc, 0x20000, v74
	v_addc_co_u32_e32 v75, vcc, 0, v75, vcc
	global_load_dword v67, v[76:77], off offset:656
	global_load_dword v44, v[74:75], off
	v_add_co_u32_e32 v74, vcc, 0x20000, v74
	v_addc_co_u32_e32 v75, vcc, 0, v75, vcc
	global_load_dword v68, v[76:77], off offset:672
	global_load_dword v45, v[74:75], off
	v_add_co_u32_e32 v74, vcc, 0x20000, v74
	v_addc_co_u32_e32 v75, vcc, 0, v75, vcc
	global_load_dword v69, v[76:77], off offset:688
	global_load_dword v46, v[74:75], off
	v_add_co_u32_e32 v74, vcc, 0x20000, v74
	v_addc_co_u32_e32 v75, vcc, 0, v75, vcc
	global_load_dword v70, v[76:77], off offset:704
	global_load_dword v47, v[74:75], off
	v_add_co_u32_e32 v74, vcc, 0x20000, v74
	v_addc_co_u32_e32 v75, vcc, 0, v75, vcc
	global_load_dword v71, v[76:77], off offset:720
	global_load_dword v48, v[74:75], off
	v_add_co_u32_e32 v74, vcc, 0x20000, v74
	v_addc_co_u32_e32 v75, vcc, 0, v75, vcc
	global_load_dword v72, v[76:77], off offset:736
	global_load_dword v49, v[74:75], off
	v_add_co_u32_e32 v74, vcc, 0x20000, v74
	v_addc_co_u32_e32 v75, vcc, 0, v75, vcc
	global_load_dword v73, v[76:77], off offset:752
	s_waitcnt vmcnt(40)
	v_cvt_pk_bf16_f32 v80, v49, v11
	v_mul_f32_e32 v81, 0x3fb8aa3b, v50
	global_store_short v[78:79], v80, off
	v_exp_f32_e32 v81, v81
	v_add_co_u32_e32 v78, vcc, 0x10000, v78
	v_addc_co_u32_e32 v79, vcc, 0, v79, vcc
	v_fmac_f32_e32 v26, v49, v81
	v_cvt_pk_bf16_f32 v80, v26, v11
	v_mul_f32_e32 v81, 0x3fb8aa3b, v51
	global_store_short v[78:79], v80, off
	v_exp_f32_e32 v81, v81
	v_add_co_u32_e32 v78, vcc, 0x10000, v78
	v_addc_co_u32_e32 v79, vcc, 0, v79, vcc
	v_fmac_f32_e32 v27, v26, v81
	v_cvt_pk_bf16_f32 v80, v27, v11
	v_mul_f32_e32 v81, 0x3fb8aa3b, v52
	global_store_short v[78:79], v80, off
	v_exp_f32_e32 v81, v81
	v_add_co_u32_e32 v78, vcc, 0x10000, v78
	v_addc_co_u32_e32 v79, vcc, 0, v79, vcc
	v_fmac_f32_e32 v28, v27, v81
	v_cvt_pk_bf16_f32 v80, v28, v11
	v_mul_f32_e32 v81, 0x3fb8aa3b, v53
	global_store_short v[78:79], v80, off
	v_exp_f32_e32 v81, v81
	v_add_co_u32_e32 v78, vcc, 0x10000, v78
	v_addc_co_u32_e32 v79, vcc, 0, v79, vcc
	v_fmac_f32_e32 v29, v28, v81
	v_cvt_pk_bf16_f32 v80, v29, v11
	v_mul_f32_e32 v81, 0x3fb8aa3b, v54
	global_store_short v[78:79], v80, off
	v_exp_f32_e32 v81, v81
	v_add_co_u32_e32 v78, vcc, 0x10000, v78
	v_addc_co_u32_e32 v79, vcc, 0, v79, vcc
	v_fmac_f32_e32 v30, v29, v81
	v_cvt_pk_bf16_f32 v80, v30, v11
	v_mul_f32_e32 v81, 0x3fb8aa3b, v55
	global_store_short v[78:79], v80, off
	v_exp_f32_e32 v81, v81
	v_add_co_u32_e32 v78, vcc, 0x10000, v78
	v_addc_co_u32_e32 v79, vcc, 0, v79, vcc
	v_fmac_f32_e32 v31, v30, v81
	v_cvt_pk_bf16_f32 v80, v31, v11
	v_mul_f32_e32 v81, 0x3fb8aa3b, v56
	global_store_short v[78:79], v80, off
	v_exp_f32_e32 v81, v81
	v_add_co_u32_e32 v78, vcc, 0x10000, v78
	v_addc_co_u32_e32 v79, vcc, 0, v79, vcc
	v_fmac_f32_e32 v32, v31, v81
	v_cvt_pk_bf16_f32 v80, v32, v11
	v_mul_f32_e32 v81, 0x3fb8aa3b, v57
	global_store_short v[78:79], v80, off
	v_exp_f32_e32 v81, v81
	v_add_co_u32_e32 v78, vcc, 0x10000, v78
	v_addc_co_u32_e32 v79, vcc, 0, v79, vcc
	v_fmac_f32_e32 v33, v32, v81
	global_load_dword v26, v[74:75], off
	v_add_co_u32_e32 v74, vcc, 0x20000, v74
	v_addc_co_u32_e32 v75, vcc, 0, v75, vcc
	global_load_dword v50, v[76:77], off offset:768
	global_load_dword v27, v[74:75], off
	v_add_co_u32_e32 v74, vcc, 0x20000, v74
	v_addc_co_u32_e32 v75, vcc, 0, v75, vcc
	global_load_dword v51, v[76:77], off offset:784
	global_load_dword v28, v[74:75], off
	v_add_co_u32_e32 v74, vcc, 0x20000, v74
	v_addc_co_u32_e32 v75, vcc, 0, v75, vcc
	global_load_dword v52, v[76:77], off offset:800
	global_load_dword v29, v[74:75], off
	v_add_co_u32_e32 v74, vcc, 0x20000, v74
	v_addc_co_u32_e32 v75, vcc, 0, v75, vcc
	global_load_dword v53, v[76:77], off offset:816
	global_load_dword v30, v[74:75], off
	v_add_co_u32_e32 v74, vcc, 0x20000, v74
	v_addc_co_u32_e32 v75, vcc, 0, v75, vcc
	global_load_dword v54, v[76:77], off offset:832
	global_load_dword v31, v[74:75], off
	v_add_co_u32_e32 v74, vcc, 0x20000, v74
	v_addc_co_u32_e32 v75, vcc, 0, v75, vcc
	global_load_dword v55, v[76:77], off offset:848
	global_load_dword v32, v[74:75], off
	v_add_co_u32_e32 v74, vcc, 0x20000, v74
	v_addc_co_u32_e32 v75, vcc, 0, v75, vcc
	global_load_dword v56, v[76:77], off offset:864
	global_load_dword v33, v[74:75], off
	v_add_co_u32_e32 v74, vcc, 0x20000, v74
	v_addc_co_u32_e32 v75, vcc, 0, v75, vcc
	global_load_dword v57, v[76:77], off offset:880
	s_waitcnt vmcnt(40)
	v_cvt_pk_bf16_f32 v80, v33, v11
	v_mul_f32_e32 v81, 0x3fb8aa3b, v58
	global_store_short v[78:79], v80, off
	v_exp_f32_e32 v81, v81
	v_add_co_u32_e32 v78, vcc, 0x10000, v78
	v_addc_co_u32_e32 v79, vcc, 0, v79, vcc
	v_fmac_f32_e32 v34, v33, v81
	v_cvt_pk_bf16_f32 v80, v34, v11
	v_mul_f32_e32 v81, 0x3fb8aa3b, v59
	global_store_short v[78:79], v80, off
	v_exp_f32_e32 v81, v81
	v_add_co_u32_e32 v78, vcc, 0x10000, v78
	v_addc_co_u32_e32 v79, vcc, 0, v79, vcc
	v_fmac_f32_e32 v35, v34, v81
	v_cvt_pk_bf16_f32 v80, v35, v11
	v_mul_f32_e32 v81, 0x3fb8aa3b, v60
	global_store_short v[78:79], v80, off
	v_exp_f32_e32 v81, v81
	v_add_co_u32_e32 v78, vcc, 0x10000, v78
	v_addc_co_u32_e32 v79, vcc, 0, v79, vcc
	v_fmac_f32_e32 v36, v35, v81
	v_cvt_pk_bf16_f32 v80, v36, v11
	v_mul_f32_e32 v81, 0x3fb8aa3b, v61
	global_store_short v[78:79], v80, off
	v_exp_f32_e32 v81, v81
	v_add_co_u32_e32 v78, vcc, 0x10000, v78
	v_addc_co_u32_e32 v79, vcc, 0, v79, vcc
	v_fmac_f32_e32 v37, v36, v81
	v_cvt_pk_bf16_f32 v80, v37, v11
	v_mul_f32_e32 v81, 0x3fb8aa3b, v62
	global_store_short v[78:79], v80, off
	v_exp_f32_e32 v81, v81
	v_add_co_u32_e32 v78, vcc, 0x10000, v78
	v_addc_co_u32_e32 v79, vcc, 0, v79, vcc
	v_fmac_f32_e32 v38, v37, v81
	v_cvt_pk_bf16_f32 v80, v38, v11
	v_mul_f32_e32 v81, 0x3fb8aa3b, v63
	global_store_short v[78:79], v80, off
	v_exp_f32_e32 v81, v81
	v_add_co_u32_e32 v78, vcc, 0x10000, v78
	v_addc_co_u32_e32 v79, vcc, 0, v79, vcc
	v_fmac_f32_e32 v39, v38, v81
	v_cvt_pk_bf16_f32 v80, v39, v11
	v_mul_f32_e32 v81, 0x3fb8aa3b, v64
	global_store_short v[78:79], v80, off
	v_exp_f32_e32 v81, v81
	v_add_co_u32_e32 v78, vcc, 0x10000, v78
	v_addc_co_u32_e32 v79, vcc, 0, v79, vcc
	v_fmac_f32_e32 v40, v39, v81
	v_cvt_pk_bf16_f32 v80, v40, v11
	v_mul_f32_e32 v81, 0x3fb8aa3b, v65
	global_store_short v[78:79], v80, off
	v_exp_f32_e32 v81, v81
	v_add_co_u32_e32 v78, vcc, 0x10000, v78
	v_addc_co_u32_e32 v79, vcc, 0, v79, vcc
	v_fmac_f32_e32 v41, v40, v81
	global_load_dword v34, v[74:75], off
	v_add_co_u32_e32 v74, vcc, 0x20000, v74
	v_addc_co_u32_e32 v75, vcc, 0, v75, vcc
	global_load_dword v58, v[76:77], off offset:896
	global_load_dword v35, v[74:75], off
	v_add_co_u32_e32 v74, vcc, 0x20000, v74
	v_addc_co_u32_e32 v75, vcc, 0, v75, vcc
	global_load_dword v59, v[76:77], off offset:912
	global_load_dword v36, v[74:75], off
	v_add_co_u32_e32 v74, vcc, 0x20000, v74
	v_addc_co_u32_e32 v75, vcc, 0, v75, vcc
	global_load_dword v60, v[76:77], off offset:928
	global_load_dword v37, v[74:75], off
	v_add_co_u32_e32 v74, vcc, 0x20000, v74
	v_addc_co_u32_e32 v75, vcc, 0, v75, vcc
	global_load_dword v61, v[76:77], off offset:944
	global_load_dword v38, v[74:75], off
	v_add_co_u32_e32 v74, vcc, 0x20000, v74
	v_addc_co_u32_e32 v75, vcc, 0, v75, vcc
	global_load_dword v62, v[76:77], off offset:960
	global_load_dword v39, v[74:75], off
	v_add_co_u32_e32 v74, vcc, 0x20000, v74
	v_addc_co_u32_e32 v75, vcc, 0, v75, vcc
	global_load_dword v63, v[76:77], off offset:976
	global_load_dword v40, v[74:75], off
	v_add_co_u32_e32 v74, vcc, 0x20000, v74
	v_addc_co_u32_e32 v75, vcc, 0, v75, vcc
	global_load_dword v64, v[76:77], off offset:992
	global_load_dword v41, v[74:75], off
	v_add_co_u32_e32 v74, vcc, 0x20000, v74
	v_addc_co_u32_e32 v75, vcc, 0, v75, vcc
	global_load_dword v65, v[76:77], off offset:1008
	s_waitcnt vmcnt(40)
	v_cvt_pk_bf16_f32 v80, v41, v11
	v_mul_f32_e32 v81, 0x3fb8aa3b, v66
	global_store_short v[78:79], v80, off
	v_exp_f32_e32 v81, v81
	v_add_co_u32_e32 v78, vcc, 0x10000, v78
	v_addc_co_u32_e32 v79, vcc, 0, v79, vcc
	v_fmac_f32_e32 v42, v41, v81
	v_cvt_pk_bf16_f32 v80, v42, v11
	v_mul_f32_e32 v81, 0x3fb8aa3b, v67
	global_store_short v[78:79], v80, off
	v_exp_f32_e32 v81, v81
	v_add_co_u32_e32 v78, vcc, 0x10000, v78
	v_addc_co_u32_e32 v79, vcc, 0, v79, vcc
	v_fmac_f32_e32 v43, v42, v81
	v_cvt_pk_bf16_f32 v80, v43, v11
	v_mul_f32_e32 v81, 0x3fb8aa3b, v68
	global_store_short v[78:79], v80, off
	v_exp_f32_e32 v81, v81
	v_add_co_u32_e32 v78, vcc, 0x10000, v78
	v_addc_co_u32_e32 v79, vcc, 0, v79, vcc
	v_fmac_f32_e32 v44, v43, v81
	v_cvt_pk_bf16_f32 v80, v44, v11
	v_mul_f32_e32 v81, 0x3fb8aa3b, v69
	global_store_short v[78:79], v80, off
	v_exp_f32_e32 v81, v81
	v_add_co_u32_e32 v78, vcc, 0x10000, v78
	v_addc_co_u32_e32 v79, vcc, 0, v79, vcc
	v_fmac_f32_e32 v45, v44, v81
	v_cvt_pk_bf16_f32 v80, v45, v11
	v_mul_f32_e32 v81, 0x3fb8aa3b, v70
	global_store_short v[78:79], v80, off
	v_exp_f32_e32 v81, v81
	v_add_co_u32_e32 v78, vcc, 0x10000, v78
	v_addc_co_u32_e32 v79, vcc, 0, v79, vcc
	v_fmac_f32_e32 v46, v45, v81
	v_cvt_pk_bf16_f32 v80, v46, v11
	v_mul_f32_e32 v81, 0x3fb8aa3b, v71
	global_store_short v[78:79], v80, off
	v_exp_f32_e32 v81, v81
	v_add_co_u32_e32 v78, vcc, 0x10000, v78
	v_addc_co_u32_e32 v79, vcc, 0, v79, vcc
	v_fmac_f32_e32 v47, v46, v81
	v_cvt_pk_bf16_f32 v80, v47, v11
	v_mul_f32_e32 v81, 0x3fb8aa3b, v72
	global_store_short v[78:79], v80, off
	v_exp_f32_e32 v81, v81
	v_add_co_u32_e32 v78, vcc, 0x10000, v78
	v_addc_co_u32_e32 v79, vcc, 0, v79, vcc
	v_fmac_f32_e32 v48, v47, v81
	v_cvt_pk_bf16_f32 v80, v48, v11
	v_mul_f32_e32 v81, 0x3fb8aa3b, v73
	global_store_short v[78:79], v80, off
	v_exp_f32_e32 v81, v81
	v_add_co_u32_e32 v78, vcc, 0x10000, v78
	v_addc_co_u32_e32 v79, vcc, 0, v79, vcc
	v_fmac_f32_e32 v49, v48, v81
	s_waitcnt vmcnt(24)
	v_cvt_pk_bf16_f32 v80, v49, v11
	v_mul_f32_e32 v81, 0x3fb8aa3b, v50
	global_store_short v[78:79], v80, off
	v_exp_f32_e32 v81, v81
	v_add_co_u32_e32 v78, vcc, 0x10000, v78
	v_addc_co_u32_e32 v79, vcc, 0, v79, vcc
	v_fmac_f32_e32 v26, v49, v81
	v_cvt_pk_bf16_f32 v80, v26, v11
	v_mul_f32_e32 v81, 0x3fb8aa3b, v51
	global_store_short v[78:79], v80, off
	v_exp_f32_e32 v81, v81
	v_add_co_u32_e32 v78, vcc, 0x10000, v78
	v_addc_co_u32_e32 v79, vcc, 0, v79, vcc
	v_fmac_f32_e32 v27, v26, v81
	v_cvt_pk_bf16_f32 v80, v27, v11
	v_mul_f32_e32 v81, 0x3fb8aa3b, v52
	global_store_short v[78:79], v80, off
	v_exp_f32_e32 v81, v81
	v_add_co_u32_e32 v78, vcc, 0x10000, v78
	v_addc_co_u32_e32 v79, vcc, 0, v79, vcc
	v_fmac_f32_e32 v28, v27, v81
	v_cvt_pk_bf16_f32 v80, v28, v11
	v_mul_f32_e32 v81, 0x3fb8aa3b, v53
	global_store_short v[78:79], v80, off
	v_exp_f32_e32 v81, v81
	v_add_co_u32_e32 v78, vcc, 0x10000, v78
	v_addc_co_u32_e32 v79, vcc, 0, v79, vcc
	v_fmac_f32_e32 v29, v28, v81
	v_cvt_pk_bf16_f32 v80, v29, v11
	v_mul_f32_e32 v81, 0x3fb8aa3b, v54
	global_store_short v[78:79], v80, off
	v_exp_f32_e32 v81, v81
	v_add_co_u32_e32 v78, vcc, 0x10000, v78
	v_addc_co_u32_e32 v79, vcc, 0, v79, vcc
	v_fmac_f32_e32 v30, v29, v81
	v_cvt_pk_bf16_f32 v80, v30, v11
	v_mul_f32_e32 v81, 0x3fb8aa3b, v55
	global_store_short v[78:79], v80, off
	v_exp_f32_e32 v81, v81
	v_add_co_u32_e32 v78, vcc, 0x10000, v78
	v_addc_co_u32_e32 v79, vcc, 0, v79, vcc
	v_fmac_f32_e32 v31, v30, v81
	v_cvt_pk_bf16_f32 v80, v31, v11
	v_mul_f32_e32 v81, 0x3fb8aa3b, v56
	global_store_short v[78:79], v80, off
	v_exp_f32_e32 v81, v81
	v_add_co_u32_e32 v78, vcc, 0x10000, v78
	v_addc_co_u32_e32 v79, vcc, 0, v79, vcc
	v_fmac_f32_e32 v32, v31, v81
	v_cvt_pk_bf16_f32 v80, v32, v11
	v_mul_f32_e32 v81, 0x3fb8aa3b, v57
	global_store_short v[78:79], v80, off
	v_exp_f32_e32 v81, v81
	v_add_co_u32_e32 v78, vcc, 0x10000, v78
	v_addc_co_u32_e32 v79, vcc, 0, v79, vcc
	v_fmac_f32_e32 v33, v32, v81
	s_waitcnt vmcnt(8)
	v_cvt_pk_bf16_f32 v80, v33, v11
	v_mul_f32_e32 v81, 0x3fb8aa3b, v58
	global_store_short v[78:79], v80, off
	v_exp_f32_e32 v81, v81
	v_add_co_u32_e32 v78, vcc, 0x10000, v78
	v_addc_co_u32_e32 v79, vcc, 0, v79, vcc
	v_fmac_f32_e32 v34, v33, v81
	v_cvt_pk_bf16_f32 v80, v34, v11
	v_mul_f32_e32 v81, 0x3fb8aa3b, v59
	global_store_short v[78:79], v80, off
	v_exp_f32_e32 v81, v81
	v_add_co_u32_e32 v78, vcc, 0x10000, v78
	v_addc_co_u32_e32 v79, vcc, 0, v79, vcc
	v_fmac_f32_e32 v35, v34, v81
	v_cvt_pk_bf16_f32 v80, v35, v11
	v_mul_f32_e32 v81, 0x3fb8aa3b, v60
	global_store_short v[78:79], v80, off
	v_exp_f32_e32 v81, v81
	v_add_co_u32_e32 v78, vcc, 0x10000, v78
	v_addc_co_u32_e32 v79, vcc, 0, v79, vcc
	v_fmac_f32_e32 v36, v35, v81
	v_cvt_pk_bf16_f32 v80, v36, v11
	v_mul_f32_e32 v81, 0x3fb8aa3b, v61
	global_store_short v[78:79], v80, off
	v_exp_f32_e32 v81, v81
	v_add_co_u32_e32 v78, vcc, 0x10000, v78
	v_addc_co_u32_e32 v79, vcc, 0, v79, vcc
	v_fmac_f32_e32 v37, v36, v81
	v_cvt_pk_bf16_f32 v80, v37, v11
	v_mul_f32_e32 v81, 0x3fb8aa3b, v62
	global_store_short v[78:79], v80, off
	v_exp_f32_e32 v81, v81
	v_add_co_u32_e32 v78, vcc, 0x10000, v78
	v_addc_co_u32_e32 v79, vcc, 0, v79, vcc
	v_fmac_f32_e32 v38, v37, v81
	v_cvt_pk_bf16_f32 v80, v38, v11
	v_mul_f32_e32 v81, 0x3fb8aa3b, v63
	global_store_short v[78:79], v80, off
	v_exp_f32_e32 v81, v81
	v_add_co_u32_e32 v78, vcc, 0x10000, v78
	v_addc_co_u32_e32 v79, vcc, 0, v79, vcc
	v_fmac_f32_e32 v39, v38, v81
	v_cvt_pk_bf16_f32 v80, v39, v11
	v_mul_f32_e32 v81, 0x3fb8aa3b, v64
	global_store_short v[78:79], v80, off
	v_exp_f32_e32 v81, v81
	v_add_co_u32_e32 v78, vcc, 0x10000, v78
	v_addc_co_u32_e32 v79, vcc, 0, v79, vcc
	v_fmac_f32_e32 v40, v39, v81
	v_cvt_pk_bf16_f32 v80, v40, v11
	v_mul_f32_e32 v81, 0x3fb8aa3b, v65
	global_store_short v[78:79], v80, off
	v_exp_f32_e32 v81, v81
	v_add_co_u32_e32 v78, vcc, 0x10000, v78
	v_addc_co_u32_e32 v79, vcc, 0, v79, vcc
	v_fmac_f32_e32 v41, v40, v81
	v_mov_b32_e32 v12, v41
	v_readlane_b32 s4, v243, 17
	s_mov_b32 s2, 0xffff
	s_nop 0
	v_add_u32_e32 v8, s4, v8
	v_cmp_lt_i32_e32 vcc, s2, v8
	s_or_b64 s[10:11], vcc, s[10:11]
	v_add_u16_e32 v9, s4, v9
	s_andn2_b64 exec, exec, s[10:11]
	s_cbranch_execnz .LBB0_729
